# DIFF: next-tile skip/mask decision and K-fragment addresses precomputed under PV(sub1) MFMAs, tile top reduced to scalar flags
# baseline (speedup 1.0000x reference)
; DI u32 pk2(float a, float b) { f2_t v = {a, b}; bf2_t r = __builtin_convertvector(v, bf2_t); return __builtin_bit_cast(u32, r); }
; DI float bflo(u32 u) { return __uint_as_float(u << 16); }
; DI float bfhi(u32 u) { return __uint_as_float(u & 0xffff0000u); }
; DI float xor32_sum(float v) { auto rr = __builtin_amdgcn_permlane32_swap(__float_as_uint(v), __float_as_uint(v), false, false); return __uint_as_float(rr[0]) + __uint_as_float(rr[1]); }
; DI void pinu(u32& x) { asm volatile("" : "+v"(x)); }
; template <bool DIFF>
; DI void attn_phase(const AttnArgs& a, char* lds) {
;     ...
;       qposf = (float)a.pos[qrow];
;       u32 qo = (u32)qrow * (u32)a.ldq + (u32)((DIFF ? (h * 2 + comp) * 128 : h * 192) + (tq >> 5) * 8); pinu(qo);
; #pragma unroll
;       for (int ds = 0; ds < NDS; ++ds) qf[ds] = *(const bf16x8*)(a.Q + qo + ds * 16);
;       if (DIFF) {
;         float ss = 0.f;
; #pragma unroll
;         for (int ds = 0; ds < NDS; ++ds) {
;           const u32x4 w = __builtin_bit_cast(u32x4, qf[ds]);
; #pragma unroll
;           for (int i = 0; i < 4; ++i) { const float x0 = bflo(w[i]), x1 = bfhi(w[i]); ss += x0 * x0 + x1 * x1; }
;         }
;         ss = xor32_sum(ss);
;         const float ri = rsqrtf(ss * (1.0f / 128.0f) + EPS) * QSCALE_B;
; #pragma unroll
;         for (int ds = 0; ds < NDS; ++ds) {
;           const u32x4 w = __builtin_bit_cast(u32x4, qf[ds]);
;           const float4 ga = *(const float4*)(a.qgain + ds * 16 + (tq >> 5) * 8), gb = *(const float4*)(a.qgain + ds * 16 + (tq >> 5) * 8 + 4);
;           u32x4 o4;
;           o4[0] = pk2(bflo(w[0]) * ri * ga.x, bfhi(w[0]) * ri * ga.y); o4[1] = pk2(bflo(w[1]) * ri * ga.z, bfhi(w[1]) * ri * ga.w);
;           o4[2] = pk2(bflo(w[2]) * ri * gb.x, bfhi(w[2]) * ri * gb.y); o4[3] = pk2(bflo(w[3]) * ri * gb.z, bfhi(w[3]) * ri * gb.w);
;           qf[ds] = __builtin_bit_cast(bf16x8, o4);
;         }
.LBB0_597:
	s_andn2_b64 vcc, exec, s[66:67]
	s_waitcnt vmcnt(0) lgkmcnt(0)
	s_barrier
	s_cbranch_vccnz .LBB0_630
	v_add_f32_e32 v0, v136, v87
	v_fmamk_f32 v0, v0, 0x3c000000, v212
	v_mul_f32_e32 v87, 0x4b800000, v0
	v_cmp_gt_f32_e32 vcc, s72, v0
	v_mov_b32_e32 v89, v95
	v_mov_b32_e32 v95, v117
	v_cndmask_b32_e32 v0, v0, v87, vcc
	v_rsq_f32_e32 v0, v0
	v_mov_b32_e32 v87, v97
	v_mov_b32_e32 v97, v119
	v_mov_b32_e32 v91, v93
	v_mul_f32_e32 v116, 0x45800000, v0
	v_cndmask_b32_e32 v0, v0, v116, vcc
	v_mul_f32_e32 v0, 0x3e0293ee, v0
	v_pk_mul_f32 v[116:117], v[0:1], v[134:135] op_sel_hi:[0,1]
	v_pk_mul_f32 v[62:63], v[62:63], v[116:117]
	v_mov_b32_e32 v93, v123
	v_cvt_pk_bf16_f32 v176, v62, v63
	v_pk_mul_f32 v[62:63], v[0:1], v[132:133] op_sel_hi:[0,1]
	v_pk_mul_f32 v[62:63], v[64:65], v[62:63]
	s_add_i32 s4, s0, 1
	v_cvt_pk_bf16_f32 v177, v62, v63
	v_pk_mul_f32 v[62:63], v[0:1], v[130:131] op_sel_hi:[0,1]
	v_pk_mul_f32 v[58:59], v[58:59], v[62:63]
	v_cvt_f32_i32_e32 v221, v138
	v_cvt_pk_bf16_f32 v178, v58, v59
	v_pk_mul_f32 v[58:59], v[0:1], v[128:129] op_sel_hi:[0,1]
	v_pk_mul_f32 v[58:59], v[60:61], v[58:59]
	v_cndmask_b32_e64 v222, 0, 1, s[8:9]
	v_cvt_pk_bf16_f32 v179, v58, v59
	v_pk_mul_f32 v[58:59], v[0:1], v[126:127] op_sel_hi:[0,1]
	v_pk_mul_f32 v[54:55], v[54:55], v[58:59]
	v_cndmask_b32_e64 v225, v215, 0, s[8:9]
	v_cvt_pk_bf16_f32 v180, v54, v55
	v_pk_mul_f32 v[54:55], v[0:1], v[124:125] op_sel_hi:[0,1]
	v_pk_mul_f32 v[54:55], v[56:57], v[54:55]
	v_mov_b32_e32 v226, 0
	v_cvt_pk_bf16_f32 v181, v54, v55
	v_pk_mul_f32 v[54:55], v[0:1], v[120:121] op_sel_hi:[0,1]
	v_pk_mul_f32 v[50:51], v[54:55], v[50:51]
	s_nop 0
	v_cvt_pk_bf16_f32 v182, v50, v51
	v_pk_mul_f32 v[50:51], v[0:1], v[66:67] op_sel_hi:[0,1]
	v_pk_mul_f32 v[50:51], v[50:51], v[52:53]
	s_nop 0
	v_cvt_pk_bf16_f32 v183, v50, v51
	v_pk_mul_f32 v[50:51], v[0:1], v[114:115] op_sel_hi:[0,1]
	v_pk_mul_f32 v[46:47], v[50:51], v[46:47]
	s_nop 0
	v_cvt_pk_bf16_f32 v184, v46, v47
	v_pk_mul_f32 v[46:47], v[0:1], v[68:69] op_sel_hi:[0,1]
	v_pk_mul_f32 v[46:47], v[46:47], v[48:49]
	s_nop 0
	v_cvt_pk_bf16_f32 v185, v46, v47
	v_pk_mul_f32 v[46:47], v[0:1], v[112:113] op_sel_hi:[0,1]
	v_pk_mul_f32 v[42:43], v[46:47], v[42:43]
	s_nop 0
	v_cvt_pk_bf16_f32 v186, v42, v43
	v_pk_mul_f32 v[42:43], v[0:1], v[70:71] op_sel_hi:[0,1]
	v_pk_mul_f32 v[42:43], v[42:43], v[44:45]
	s_nop 0
	v_cvt_pk_bf16_f32 v187, v42, v43
	v_pk_mul_f32 v[42:43], v[0:1], v[110:111] op_sel_hi:[0,1]
	v_pk_mul_f32 v[38:39], v[42:43], v[38:39]
	s_nop 0
	v_cvt_pk_bf16_f32 v188, v38, v39
	v_pk_mul_f32 v[38:39], v[0:1], v[72:73] op_sel_hi:[0,1]
	v_pk_mul_f32 v[38:39], v[38:39], v[40:41]
	s_nop 0
	v_cvt_pk_bf16_f32 v189, v38, v39
	v_pk_mul_f32 v[38:39], v[0:1], v[108:109] op_sel_hi:[0,1]
	v_pk_mul_f32 v[34:35], v[38:39], v[34:35]
	s_nop 0
	v_cvt_pk_bf16_f32 v190, v34, v35
	v_pk_mul_f32 v[34:35], v[0:1], v[74:75] op_sel_hi:[0,1]
	v_pk_mul_f32 v[34:35], v[34:35], v[36:37]
	s_nop 0
	v_cvt_pk_bf16_f32 v191, v34, v35
	v_pk_mul_f32 v[34:35], v[0:1], v[106:107] op_sel_hi:[0,1]
	v_pk_mul_f32 v[30:31], v[34:35], v[30:31]
	s_nop 0
	v_cvt_pk_bf16_f32 v192, v30, v31
	v_pk_mul_f32 v[30:31], v[0:1], v[76:77] op_sel_hi:[0,1]
	v_pk_mul_f32 v[30:31], v[30:31], v[32:33]
	s_nop 0
	v_cvt_pk_bf16_f32 v193, v30, v31
	v_pk_mul_f32 v[30:31], v[0:1], v[104:105] op_sel_hi:[0,1]
	v_pk_mul_f32 v[26:27], v[30:31], v[26:27]
	s_nop 0
	v_cvt_pk_bf16_f32 v194, v26, v27
	v_pk_mul_f32 v[26:27], v[0:1], v[78:79] op_sel_hi:[0,1]
	v_pk_mul_f32 v[26:27], v[26:27], v[28:29]
	s_nop 0
	v_cvt_pk_bf16_f32 v195, v26, v27
	v_pk_mul_f32 v[26:27], v[0:1], v[102:103] op_sel_hi:[0,1]
	v_pk_mul_f32 v[22:23], v[26:27], v[22:23]
	s_nop 0
	v_cvt_pk_bf16_f32 v196, v22, v23
	v_pk_mul_f32 v[22:23], v[0:1], v[80:81] op_sel_hi:[0,1]
	v_pk_mul_f32 v[22:23], v[22:23], v[24:25]
	s_nop 0
	v_cvt_pk_bf16_f32 v197, v22, v23
	v_pk_mul_f32 v[22:23], v[0:1], v[100:101] op_sel_hi:[0,1]
	v_pk_mul_f32 v[18:19], v[22:23], v[18:19]
	s_nop 0
	v_cvt_pk_bf16_f32 v198, v18, v19
	v_pk_mul_f32 v[18:19], v[0:1], v[82:83] op_sel_hi:[0,1]
	v_pk_mul_f32 v[18:19], v[18:19], v[20:21]
	s_nop 0
	v_cvt_pk_bf16_f32 v199, v18, v19
	v_pk_mul_f32 v[18:19], v[0:1], v[98:99] op_sel_hi:[0,1]
	v_pk_mul_f32 v[14:15], v[18:19], v[14:15]
	s_nop 0
	v_cvt_pk_bf16_f32 v200, v14, v15
	v_pk_mul_f32 v[14:15], v[0:1], v[84:85] op_sel_hi:[0,1]
	v_pk_mul_f32 v[14:15], v[14:15], v[16:17]
	s_nop 0
	v_cvt_pk_bf16_f32 v201, v14, v15
	v_pk_mul_f32 v[14:15], v[0:1], v[96:97] op_sel_hi:[0,1]
	v_pk_mul_f32 v[10:11], v[14:15], v[10:11]
	v_mov_b32_e32 v14, v1
	v_cvt_pk_bf16_f32 v202, v10, v11
	v_pk_mul_f32 v[10:11], v[0:1], v[86:87] op_sel_hi:[0,1]
	v_pk_mul_f32 v[10:11], v[10:11], v[12:13]
	v_mov_b32_e32 v15, v1
	v_cvt_pk_bf16_f32 v203, v10, v11
	v_pk_mul_f32 v[10:11], v[0:1], v[94:95] op_sel_hi:[0,1]
	v_pk_mul_f32 v[6:7], v[10:11], v[6:7]
	v_mov_b32_e32 v10, v1
	v_cvt_pk_bf16_f32 v204, v6, v7
	v_pk_mul_f32 v[6:7], v[0:1], v[88:89] op_sel_hi:[0,1]
	v_pk_mul_f32 v[6:7], v[6:7], v[8:9]
	v_mov_b32_e32 v8, v1
	v_cvt_pk_bf16_f32 v205, v6, v7
	v_pk_mul_f32 v[6:7], v[0:1], v[92:93] op_sel_hi:[0,1]
	v_pk_mul_f32 v[2:3], v[6:7], v[2:3]
	v_cvt_f32_i32_e32 v6, s4
	v_cvt_pk_bf16_f32 v206, v2, v3
	v_pk_mul_f32 v[2:3], v[0:1], v[90:91] op_sel_hi:[0,1]
	v_pk_mul_f32 v[2:3], v[2:3], v[4:5]
; #define GLDS16(g, l) __builtin_amdgcn_global_load_lds((const unsigned*)(g), (unsigned*)(l), 16, 0, 0)
; #define GLDS4(g, l) __builtin_amdgcn_global_load_lds((const unsigned*)(g), (unsigned*)(l), 4, 0, 0)
; DI int tid_pinned() { int t = threadIdx.x; asm volatile("" : "+v"(t)); return t; }
; template <bool DIFF>
; DI void attn_phase(const AttnArgs& a, char* lds) {
;     ...
;     const float slope2 = DIFF ? exp2f(-(float)(h + 1)) * LOG2E : 0.f;
;     ...
;     f32x16 o[NM];
; #pragma unroll
;     for (int m = 0; m < NM; ++m)
; #pragma unroll
;       for (int r = 0; r < 16; ++r) o[m][r] = 0.f;
;     const float sbound = a.lamtab_all[DIFF ? 4 : 3];
;     const int usefix_i = __builtin_amdgcn_readfirstlane(sbound < 40.0f ? 1 : 0);
;     const bool usefix = usefix_i != 0;
;     float m_ref = usefix ? 0.f : -1e30f, l_sum = 0.f;
;     f32x16 negm;
; #pragma unroll
;     for (int r = 0; r < 16; ++r) negm[r] = 0.f;
;     ...
;     for (int t = t_beg; t < t_end; ++t) {
;       const char* sb = lds + (t & 1) * STAGE;
;       char* nb = lds + ((t + 1) & 1) * STAGE;
;       const bool nxt = t + 1 < t_end;
;       const int4 tinfo = *(const int4*)(ttab + 4 * t);
;       const int kcmin = __builtin_amdgcn_readfirstlane(tinfo.x), kcmax = __builtin_amdgcn_readfirstlane(tinfo.y);
;       bool skip = kcmin > wqcmax;
;       if (DIFF) {
;         const int tpmin = __builtin_amdgcn_readfirstlane(tinfo.z), tpmax = __builtin_amdgcn_readfirstlane(tinfo.w);
;         const int dist = max(0, max(wpmin - tpmax, tpmin - wpmax));
;         skip = skip || (slope2 * (float)dist > lim2);
;       }
;       const bool needmask = kcmax > wqcmin;
;       if (nxt) {
;         const int t2 = tid_pinned();
;         const u32 kofs = KOFS(t2), vofs = VOFS(t2);
;         const u32 ko2 = kofs + (u32)(t + 1) * 64u * (u32)a.ldk;
; #pragma unroll
;         for (int i = 0; i < NKR; ++i) GLDS16(a.K + ko2 + i * 64, nb + wave * 1024 + 8192 * i);
;         const u32 vo2 = vofs + (u32)(t + 1) * (u32)(DV * 64);
; #pragma unroll
;         for (int i = 0; i < NVR; ++i) GLDS16(a.VT + vo2 + i * 4096, nb + KBYTES + wave * 1024 + 8192 * i);
;         if (wave == 0) { const int l4 = (t + 1) * 64 + (t2 & 63); GLDS4(a.pos + l4, nb + KBYTES + VBYTES); GLDS4(a.posf + l4, nb + KBYTES + VBYTES + 256); }
;       }
	v_cmp_lt_f32_e32 vcc, s73, v6
	s_and_b64 s[4:5], vcc, exec
	s_cselect_b32 s4, 0xffffffc0, 0
	v_cndmask_b32_e32 v0, 0, v214, vcc
	v_sub_f32_e32 v0, v0, v6
	v_exp_f32_e32 v0, v0
	s_lshl_b32 s0, s0, 22
	v_cvt_pk_bf16_f32 v207, v2, v3
	v_mov_b32_e32 v2, v1
	v_ldexp_f32 v0, v0, s4
	v_mul_f32_e32 v223, 0x3fb8aa3b, v0
	v_cvt_i32_f32_e32 v0, v221
	s_lshl_b32 s4, s1, 4
	s_add_i32 s80, s4, 0x20ff0
	s_lshl_b32 s4, s1, 6
	s_add_i32 s81, s4, 64
	s_lshl_b32 s4, s1, 14
	v_ashrrev_i32_e32 v224, 6, v0
	s_add_i32 s0, s0, s4
	v_mov_b32_e32 v0, v1
	v_mov_b32_e32 v3, v1
	v_mov_b32_e32 v4, v1
	v_mov_b32_e32 v5, v1
	v_mov_b32_e32 v6, v1
	v_mov_b32_e32 v7, v1
	v_mov_b32_e32 v9, v1
	v_mov_b32_e32 v11, v1
	v_mov_b32_e32 v12, v1
	v_mov_b32_e32 v13, v1
	v_mov_b64_e32 v[30:31], v[14:15]
	v_mov_b64_e32 v[46:47], v[14:15]
	v_mov_b64_e32 v[62:63], v[14:15]
	v_mov_b64_e32 v[78:79], v[14:15]
	v_mov_b64_e32 v[94:95], v[14:15]
	v_mov_b64_e32 v[110:111], v[14:15]
	v_mov_b64_e32 v[126:127], v[14:15]
	v_mov_b64_e32 v[142:143], v[14:15]
	s_add_i32 s79, s75, 0x800
	s_add_i32 s82, s0, 0x4000
	v_mov_b64_e32 v[28:29], v[12:13]
	v_mov_b64_e32 v[26:27], v[10:11]
	v_mov_b64_e32 v[24:25], v[8:9]
	v_mov_b64_e32 v[22:23], v[6:7]
	v_mov_b64_e32 v[20:21], v[4:5]
	v_mov_b64_e32 v[18:19], v[2:3]
	v_mov_b64_e32 v[16:17], v[0:1]
	v_mov_b64_e32 v[44:45], v[12:13]
	v_mov_b64_e32 v[42:43], v[10:11]
	v_mov_b64_e32 v[40:41], v[8:9]
	v_mov_b64_e32 v[38:39], v[6:7]
	v_mov_b64_e32 v[36:37], v[4:5]
	v_mov_b64_e32 v[34:35], v[2:3]
	v_mov_b64_e32 v[32:33], v[0:1]
	v_mov_b64_e32 v[60:61], v[12:13]
	v_mov_b64_e32 v[58:59], v[10:11]
	v_mov_b64_e32 v[56:57], v[8:9]
	v_mov_b64_e32 v[54:55], v[6:7]
	v_mov_b64_e32 v[52:53], v[4:5]
	v_mov_b64_e32 v[50:51], v[2:3]
	v_mov_b64_e32 v[48:49], v[0:1]
	v_mov_b64_e32 v[76:77], v[12:13]
	v_mov_b64_e32 v[74:75], v[10:11]
	v_mov_b64_e32 v[72:73], v[8:9]
	v_mov_b64_e32 v[70:71], v[6:7]
	v_mov_b64_e32 v[68:69], v[4:5]
	v_mov_b64_e32 v[66:67], v[2:3]
	v_mov_b64_e32 v[64:65], v[0:1]
	v_mov_b64_e32 v[92:93], v[12:13]
	v_mov_b64_e32 v[90:91], v[10:11]
	v_mov_b64_e32 v[88:89], v[8:9]
	v_mov_b64_e32 v[86:87], v[6:7]
	v_mov_b64_e32 v[84:85], v[4:5]
	v_mov_b64_e32 v[82:83], v[2:3]
	v_mov_b64_e32 v[80:81], v[0:1]
	v_mov_b64_e32 v[108:109], v[12:13]
	v_mov_b64_e32 v[106:107], v[10:11]
	v_mov_b64_e32 v[104:105], v[8:9]
	v_mov_b64_e32 v[102:103], v[6:7]
	v_mov_b64_e32 v[100:101], v[4:5]
	v_mov_b64_e32 v[98:99], v[2:3]
	v_mov_b64_e32 v[96:97], v[0:1]
	v_mov_b64_e32 v[124:125], v[12:13]
	v_mov_b64_e32 v[122:123], v[10:11]
	v_mov_b64_e32 v[120:121], v[8:9]
	v_mov_b64_e32 v[118:119], v[6:7]
	v_mov_b64_e32 v[116:117], v[4:5]
	v_mov_b64_e32 v[114:115], v[2:3]
	v_mov_b64_e32 v[112:113], v[0:1]
	v_mov_b64_e32 v[140:141], v[12:13]
	v_mov_b64_e32 v[138:139], v[10:11]
	v_mov_b64_e32 v[136:137], v[8:9]
	v_mov_b64_e32 v[134:135], v[6:7]
	v_mov_b64_e32 v[132:133], v[4:5]
	v_mov_b64_e32 v[130:131], v[2:3]
	v_mov_b64_e32 v[128:129], v[0:1]
	s_mov_b32 s32, 0
.LBB0_599:
	s_add_i32 s83, s1, 1
	s_cmp_ge_i32 s83, s78
	s_cselect_b64 s[66:67], -1, 0
	s_bitcmp1_b32 s83, 0
	s_cselect_b32 s85, 0x10200, 0
	s_add_i32 s86, s85, s33
	s_cmp_eq_u32 s32, 0
	s_cbranch_scc1 .Ldiff_top_sync
	s_bitcmp1_b32 s1, 0
	s_cselect_b32 s84, 0x10200, 0
	v_mov_b32_e32 v0, v222
	s_cmp_lg_u32 s87, 0
	s_cselect_b64 s[68:69], -1, 0
	v_readfirstlane_b32 s0, v0
	s_cmp_eq_u32 s0, 0
	s_cselect_b64 s[8:9], -1, 0
	s_or_b64 s[8:9], s[8:9], s[68:69]
	s_and_b64 vcc, exec, s[8:9]
	s_cmp_lg_u32 s88, 0
	s_cselect_b64 s[8:9], -1, 0
	s_cbranch_vccnz .Ldiff_slow
	s_or_b64 vcc, s[66:67], s[6:7]
	s_and_b64 vcc, exec, vcc
	s_cbranch_vccnz .Ldiff_nw0
	v_and_b32_e32 v0, 63, v208
	v_add_u32_e32 v2, s81, v0
	v_ashrrev_i32_e32 v3, 31, v2
	v_lshlrev_b64 v[2:3], 2, v[2:3]
	v_lshl_add_u64 v[4:5], s[48:49], 0, v[2:3]
	s_add_i32 m0, s85, 0x10000
	v_lshl_add_u64 v[2:3], s[38:39], 0, v[2:3]
	global_load_lds_dword v[2:3], off
	s_add_i32 m0, s85, 0x10100
	s_nop 0
	global_load_lds_dword v[4:5], off
.Ldiff_nw0:
	v_mov_b32_e32 v2, v208
	v_lshrrev_b32_e32 v3, 1, v2
	v_bfe_u32 v0, v2, 5, 1
.Ldiff_after_f1:
	v_lshrrev_b32_e32 v209, 4, v208
	v_xor_b32_e32 v209, v209, v208
	v_lshlrev_b32_e32 v209, 3, v209
	v_and_b32_e32 v209, 56, v209
	v_ashrrev_i32_e32 v253, 3, v208
	v_lshlrev_b32_e32 v209, 1, v209
	v_lshl_add_u32 v255, v253, 7, v209
	v_lshl_add_u32 v209, v253, 13, v209
	s_lshl_b32 s87, s81, 12
	s_add_i32 s87, s87, s79
	s_lshl_b32 s87, s87, 1
	s_add_u32 s98, s30, s87
	s_addc_u32 s99, s31, 0
	s_lshl_b32 s87, s82, 1
	s_add_u32 s52, s36, s87
	s_addc_u32 s53, s37, 0
	s_and_b64 vcc, exec, s[66:67]
	v_xad_u32 v147, v145, 32, v144
	v_xad_u32 v148, v145, 64, v144
	v_xad_u32 v144, v145, s74, v144
	ds_read_b128 v[8:11], v146
	ds_read_b128 v[12:15], v147
	ds_read_b128 v[228:231], v148
	ds_read_b128 v[232:235], v144
	ds_read_b128 v[236:239], v146 offset:8192
	ds_read_b128 v[240:243], v147 offset:8192
	ds_read_b128 v[244:247], v148 offset:8192
	ds_read_b128 v[4:7], v144 offset:8192
	ds_read_b128 v[248:251], v144 offset:12288
	v_lshlrev_b32_e32 v252, 5, v0
	v_add_u32_e32 v227, s84, v252
	s_add_i32 s1, s84, 0x10000
	s_waitcnt lgkmcnt(8)
	v_mfma_f32_32x32x16_bf16 v[160:175], v[8:11], v[176:179], 0
	ds_read_b128 v[8:11], v146 offset:4096
	s_cbranch_vccnz .Ldiff_nd0
	s_mov_b32 m0, s86
	s_nop 0
	global_load_lds_dwordx4 v209, s[98:99]

; #define MFMA(a, b, c) __builtin_amdgcn_mfma_f32_32x32x16_bf16((a), (b), (c), 0, 0, 0)
; DI u32 pk2(float a, float b) { f2_t v = {a, b}; bf2_t r = __builtin_convertvector(v, bf2_t); return __builtin_bit_cast(u32, r); }
; template <bool DIFF>
; DI void attn_phase(const AttnArgs& a, char* lds) {
;     ...
;       const int4 tinfo = *(const int4*)(ttab + 4 * t);
;       const int kcmin = __builtin_amdgcn_readfirstlane(tinfo.x), kcmax = __builtin_amdgcn_readfirstlane(tinfo.y);
;       bool skip = kcmin > wqcmax;
;       if (DIFF) {
;         const int tpmin = __builtin_amdgcn_readfirstlane(tinfo.z), tpmax = __builtin_amdgcn_readfirstlane(tinfo.w);
;         const int dist = max(0, max(wpmin - tpmax, tpmin - wpmax));
;         skip = skip || (slope2 * (float)dist > lim2);
;       }
;       const bool needmask = kcmax > wqcmin;
;     ...
;         {
; #pragma unroll
;           for (int s2 = 0; s2 < 2; ++s2) {
;             bf16x8 vf[NM];
; #pragma unroll
;             for (int m = 0; m < NM; ++m) vf[m] = *(const bf16x8*)(sb + voffb + m * 4096 + (((4 + 2 * s2) ^ vx) << 4));
;             u32x4 pw;
;             pw[0] = pk2(s1[8 * s2], s1[8 * s2 + 1]); pw[1] = pk2(s1[8 * s2 + 2], s1[8 * s2 + 3]);
;             pw[2] = pk2(s1[8 * s2 + 4], s1[8 * s2 + 5]); pw[3] = pk2(s1[8 * s2 + 6], s1[8 * s2 + 7]);
;             const bf16x8 pf = __builtin_bit_cast(bf16x8, pw);
; #pragma unroll
;             for (int m = 0; m < NM; ++m) o[m] = MFMA(vf[m], pf, o[m]);
;           }
;         }
.Ldiff_nomask1:
	s_waitcnt lgkmcnt(5)
	v_mfma_f32_32x32x16_bf16 v[128:143], v[232:235], v[10:13], v[128:143]
	ds_read_b128 v[232:235], v15 offset:57344
	v_exp_f32_e32 v0, v164
	v_exp_f32_e32 v9, v165
	v_add_f32_e32 v253, 0, v0
	v_add_f32_e32 v253, v9, v253
	s_waitcnt lgkmcnt(5)
	v_mfma_f32_32x32x16_bf16 v[112:127], v[236:239], v[10:13], v[112:127]
	ds_read_b128 v[236:239], v15 offset:61440
	v_exp_f32_e32 v144, v166
	v_exp_f32_e32 v146, v167
	v_add_f32_e32 v253, v144, v253
	v_add_f32_e32 v253, v146, v253
	s_waitcnt lgkmcnt(5)
	v_mfma_f32_32x32x16_bf16 v[96:111], v[240:243], v[10:13], v[96:111]
	v_exp_f32_e32 v147, v168
	v_exp_f32_e32 v148, v169
	v_add_f32_e32 v253, v147, v253
	v_add_f32_e32 v253, v148, v253
	s_waitcnt lgkmcnt(4)
	v_mfma_f32_32x32x16_bf16 v[80:95], v[244:247], v[10:13], v[80:95]
	v_exp_f32_e32 v149, v170
	v_exp_f32_e32 v150, v171
	v_add_f32_e32 v253, v149, v253
	v_add_f32_e32 v253, v150, v253
	s_waitcnt lgkmcnt(3)
	v_mfma_f32_32x32x16_bf16 v[64:79], v[2:5], v[10:13], v[64:79]
	v_exp_f32_e32 v151, v172
	v_exp_f32_e32 v145, v173
	v_add_f32_e32 v253, v151, v253
	v_add_f32_e32 v253, v145, v253
	s_waitcnt lgkmcnt(2)
	v_mfma_f32_32x32x16_bf16 v[48:63], v[228:231], v[10:13], v[48:63]
	v_exp_f32_e32 v152, v174
	v_exp_f32_e32 v153, v175
	v_add_f32_e32 v253, v152, v253
	v_add_f32_e32 v253, v153, v253
	s_waitcnt lgkmcnt(1)
	v_mfma_f32_32x32x16_bf16 v[32:47], v[232:235], v[10:13], v[32:47]
	v_exp_f32_e32 v154, v248
	v_exp_f32_e32 v155, v249
	v_add_f32_e32 v253, v154, v253
	v_add_f32_e32 v253, v155, v253
	s_waitcnt lgkmcnt(0)
	v_mfma_f32_32x32x16_bf16 v[16:31], v[236:239], v[10:13], v[16:31]
	v_exp_f32_e32 v14, v250
	v_exp_f32_e32 v15, v251
	v_add_f32_e32 v253, v14, v253
	v_add_f32_e32 v253, v15, v253
	v_add_f32_e32 v226, v162, v253
	s_add_i32 s52, s80, 16
	v_mov_b32_e32 v164, s52
	ds_read_b128 v[164:167], v164
	v_xad_u32 v156, v161, 64, v160
	ds_read_b128 v[2:5], v156 offset:32768
	ds_read_b128 v[228:231], v156 offset:36864
	ds_read_b128 v[232:235], v156 offset:40960
	ds_read_b128 v[236:239], v156 offset:45056
	ds_read_b128 v[240:243], v156 offset:49152
	ds_read_b128 v[244:247], v156 offset:53248
	ds_read_b128 v[248:251], v156 offset:57344
	v_cvt_pk_bf16_f32 v6, v0, v9
	v_cvt_pk_bf16_f32 v7, v144, v146
	v_cvt_pk_bf16_f32 v8, v147, v148
	v_cvt_pk_bf16_f32 v9, v149, v150
	v_xad_u32 v0, v161, s74, v160
	v_cvt_pk_bf16_f32 v10, v151, v145
	v_cvt_pk_bf16_f32 v11, v152, v153
	v_cvt_pk_bf16_f32 v12, v154, v155
	v_cvt_pk_bf16_f32 v13, v14, v15
	s_waitcnt lgkmcnt(6)
	v_mfma_f32_32x32x16_bf16 v[128:143], v[2:5], v[6:9], v[128:143]
	ds_read_b128 v[2:5], v156 offset:61440
	v_readfirstlane_b32 s52, v164
	v_readfirstlane_b32 s53, v165
	v_readfirstlane_b32 s98, v166
	v_readfirstlane_b32 s99, v167
	s_waitcnt lgkmcnt(6)
	v_mfma_f32_32x32x16_bf16 v[112:127], v[228:231], v[6:9], v[112:127]
	ds_read_b128 v[228:231], v0 offset:32768
	v_subrev_u32_e32 v150, s99, v219
	v_sub_u32_e32 v151, s98, v217
	v_max3_i32 v150, v150, v151, 0
	v_cvt_f32_u32_e32 v150, v150
	s_waitcnt lgkmcnt(6)
	v_mfma_f32_32x32x16_bf16 v[96:111], v[232:235], v[6:9], v[96:111]
	ds_read_b128 v[232:235], v0 offset:36864
	v_mul_f32_e32 v150, v223, v150
	s_cmp_gt_i32 s52, s77
	s_cselect_b64 s[98:99], -1, 0
	v_cmp_gt_f32_e32 vcc, v150, v218
	s_add_i32 s52, s35, s85
	v_lshlrev_b32_e32 v149, 1, v208
	s_waitcnt lgkmcnt(6)
	v_mfma_f32_32x32x16_bf16 v[80:95], v[236:239], v[6:9], v[80:95]
	ds_read_b128 v[236:239], v0 offset:40960
	s_or_b64 s[98:99], s[98:99], vcc
	v_and_b32_e32 v150, 8, v149
	s_cmp_lg_u64 s[98:99], 0
	s_cselect_b32 s87, -1, 0
	v_cmp_gt_i32_e64 s[98:99], s53, v220
	v_lshrrev_b32_e32 v149, 1, v208
	s_waitcnt lgkmcnt(6)
	v_mfma_f32_32x32x16_bf16 v[64:79], v[240:243], v[6:9], v[64:79]
	ds_read_b128 v[240:243], v0 offset:45056
	v_and_b32_e32 v151, 4, v149
	v_and_b32_e32 v152, 19, v208
	v_or3_b32 v150, v150, v152, v151
	s_cmp_lg_u64 s[98:99], 0
	s_cselect_b32 s88, 0, -1
	s_waitcnt lgkmcnt(6)
	v_mfma_f32_32x32x16_bf16 v[48:63], v[244:247], v[6:9], v[48:63]
	ds_read_b128 v[244:247], v0 offset:49152
	v_bfe_u32 v153, v208, 5, 1
	v_lshrrev_b32_e32 v151, 1, v150
	v_bitop3_b32 v151, v151, v153, 7 bitop3:0x6c
	v_lshl_add_u32 v144, v150, 7, s52
	s_waitcnt lgkmcnt(6)
	v_mfma_f32_32x32x16_bf16 v[32:47], v[248:251], v[6:9], v[32:47]
	ds_read_b128 v[248:251], v0 offset:53248
	v_lshlrev_b32_e32 v145, 4, v151
	v_add_u32_e32 v146, v144, v145
	s_mov_b32 s32, 1
	s_waitcnt lgkmcnt(6)
	v_mfma_f32_32x32x16_bf16 v[16:31], v[2:5], v[6:9], v[16:31]
	ds_read_b128 v[2:5], v0 offset:57344
	s_waitcnt lgkmcnt(6)
	v_mfma_f32_32x32x16_bf16 v[128:143], v[228:231], v[10:13], v[128:143]
	ds_read_b128 v[228:231], v0 offset:61440
	s_waitcnt lgkmcnt(6)
	v_mfma_f32_32x32x16_bf16 v[112:127], v[232:235], v[10:13], v[112:127]
	s_waitcnt lgkmcnt(5)
	v_mfma_f32_32x32x16_bf16 v[96:111], v[236:239], v[10:13], v[96:111]
	s_waitcnt lgkmcnt(4)
	v_mfma_f32_32x32x16_bf16 v[80:95], v[240:243], v[10:13], v[80:95]
	s_waitcnt lgkmcnt(3)
	v_mfma_f32_32x32x16_bf16 v[64:79], v[244:247], v[10:13], v[64:79]
	s_waitcnt lgkmcnt(2)
	v_mfma_f32_32x32x16_bf16 v[48:63], v[248:251], v[10:13], v[48:63]
	s_waitcnt lgkmcnt(1)
	v_mfma_f32_32x32x16_bf16 v[32:47], v[2:5], v[10:13], v[32:47]
	s_waitcnt lgkmcnt(0)
	v_mfma_f32_32x32x16_bf16 v[16:31], v[228:231], v[10:13], v[16:31]

; #define GLDS16(g, l) __builtin_amdgcn_global_load_lds((const unsigned*)(g), (unsigned*)(l), 16, 0, 0)
; #define GLDS4(g, l) __builtin_amdgcn_global_load_lds((const unsigned*)(g), (unsigned*)(l), 4, 0, 0)
; DI int tid_pinned() { int t = threadIdx.x; asm volatile("" : "+v"(t)); return t; }
; template <bool DIFF>
; DI void attn_phase(const AttnArgs& a, char* lds) {
;     ...
;       const int4 tinfo = *(const int4*)(ttab + 4 * t);
;       const int kcmin = __builtin_amdgcn_readfirstlane(tinfo.x), kcmax = __builtin_amdgcn_readfirstlane(tinfo.y);
;       bool skip = kcmin > wqcmax;
;       if (DIFF) {
;         const int tpmin = __builtin_amdgcn_readfirstlane(tinfo.z), tpmax = __builtin_amdgcn_readfirstlane(tinfo.w);
;         const int dist = max(0, max(wpmin - tpmax, tpmin - wpmax));
;         skip = skip || (slope2 * (float)dist > lim2);
;       }
;       const bool needmask = kcmax > wqcmin;
;       if (nxt) {
;         const int t2 = tid_pinned();
;         const u32 kofs = KOFS(t2), vofs = VOFS(t2);
;         const u32 ko2 = kofs + (u32)(t + 1) * 64u * (u32)a.ldk;
; #pragma unroll
;         for (int i = 0; i < NKR; ++i) GLDS16(a.K + ko2 + i * 64, nb + wave * 1024 + 8192 * i);
;         const u32 vo2 = vofs + (u32)(t + 1) * (u32)(DV * 64);
; #pragma unroll
;         for (int i = 0; i < NVR; ++i) GLDS16(a.VT + vo2 + i * 4096, nb + KBYTES + wave * 1024 + 8192 * i);
;         if (wave == 0) { const int l4 = (t + 1) * 64 + (t2 & 63); GLDS4(a.pos + l4, nb + KBYTES + VBYTES); GLDS4(a.posf + l4, nb + KBYTES + VBYTES + 256); }
;       }
.Ldiff_slow:
	s_mov_b32 s32, 0
	s_and_b64 vcc, exec, s[66:67]
	s_cbranch_vccnz .LBB0_608
	v_mov_b32_e32 v2, v208
	v_lshrrev_b32_e32 v0, 4, v2
	v_xor_b32_e32 v0, v0, v2
	v_ashrrev_i32_e32 v3, 3, v2
	v_lshlrev_b32_e32 v0, 3, v0
	v_and_b32_e32 v8, 56, v0
	v_add_u32_e32 v0, s81, v3
	v_lshl_add_u32 v0, v0, 12, s79
	v_or_b32_e32 v0, v0, v8
	v_lshl_add_u64 v[4:5], v[0:1], 1, s[30:31]
	s_mov_b32 m0, s86
	v_lshl_add_u64 v[6:7], v[4:5], 0, s[42:43]
	global_load_lds_dwordx4 v[4:5], off
	s_add_i32 m0, s86, 0x2000
	v_lshl_or_b32 v0, v3, 6, v8
	global_load_lds_dwordx4 v[6:7], off
	v_lshl_add_u64 v[6:7], v[4:5], 0, s[56:57]
	s_add_i32 m0, s86, 0x4000
	v_lshl_add_u64 v[4:5], v[4:5], 0, s[58:59]
	global_load_lds_dwordx4 v[6:7], off
	s_add_i32 m0, s86, 0x6000
	v_add_u32_e32 v0, s82, v0
	global_load_lds_dwordx4 v[4:5], off
	s_add_i32 m0, s86, 0x8000
	v_lshl_add_u64 v[4:5], v[0:1], 1, s[36:37]
	global_load_lds_dwordx4 v[4:5], off
	v_lshl_add_u64 v[6:7], v[4:5], 0, s[60:61]
	s_add_i32 m0, s86, 0xa000
	s_and_b64 vcc, exec, s[6:7]
	global_load_lds_dwordx4 v[6:7], off
	v_lshl_add_u64 v[6:7], v[4:5], 0, s[62:63]
	s_add_i32 m0, s86, 0xc000
	v_lshl_add_u64 v[4:5], v[4:5], 0, s[64:65]
	global_load_lds_dwordx4 v[6:7], off
	s_add_i32 m0, s86, 0xe000
	s_nop 0
	global_load_lds_dwordx4 v[4:5], off
	s_cbranch_vccnz .LBB0_608
	v_and_b32_e32 v0, 63, v2
	v_add_u32_e32 v2, s81, v0
	v_ashrrev_i32_e32 v3, 31, v2
	v_lshlrev_b64 v[2:3], 2, v[2:3]
	v_lshl_add_u64 v[4:5], s[48:49], 0, v[2:3]
	s_add_i32 m0, s85, 0x10000
	v_lshl_add_u64 v[2:3], s[38:39], 0, v[2:3]
	global_load_lds_dword v[2:3], off
	s_add_i32 m0, s85, 0x10100
	s_nop 0
	global_load_lds_dword v[4:5], off
	s_branch .LBB0_608
.Ldiff_top_sync:
	v_mov_b32_e32 v0, s80
	ds_read_b128 v[2:5], v0
	s_waitcnt lgkmcnt(0)
	v_readfirstlane_b32 s0, v2
	v_readfirstlane_b32 s4, v3
	v_readfirstlane_b32 s5, v4
	v_readfirstlane_b32 s8, v5
	s_nop 1
	v_subrev_u32_e32 v0, s8, v219
	v_sub_u32_e32 v2, s5, v217
	v_max3_i32 v0, v0, v2, 0
	v_cvt_f32_u32_e32 v0, v0
	s_bitcmp1_b32 s1, 0
	s_cselect_b32 s84, 0x10200, 0
	s_cmp_gt_i32 s0, s77
	v_mul_f32_e32 v0, v223, v0
	s_cselect_b64 s[0:1], -1, 0
	v_cmp_gt_f32_e32 vcc, v0, v218
	v_mov_b32_e32 v0, v222
	s_or_b64 s[68:69], s[0:1], vcc
	s_nop 0
	v_readfirstlane_b32 s0, v0
	s_cmp_eq_u32 s0, 0
	s_cselect_b64 s[8:9], -1, 0
	s_or_b64 s[8:9], s[8:9], s[68:69]
	s_and_b64 vcc, exec, s[8:9]
	v_cmp_gt_i32_e64 s[8:9], s4, v220
	s_nop 1
	v_cndmask_b32_e64 v0, 0, 1, s[8:9]
	v_cmp_ne_u32_e64 s[8:9], 1, v0
	s_cbranch_vccnz .Ldiff_slow
	s_or_b64 vcc, s[66:67], s[6:7]
	s_and_b64 vcc, exec, vcc
	s_cbranch_vccnz .Ldiff_nw0b
	v_and_b32_e32 v0, 63, v208
	v_add_u32_e32 v2, s81, v0
	v_ashrrev_i32_e32 v3, 31, v2
	v_lshlrev_b64 v[2:3], 2, v[2:3]
	v_lshl_add_u64 v[4:5], s[48:49], 0, v[2:3]
	s_add_i32 m0, s85, 0x10000
	v_lshl_add_u64 v[2:3], s[38:39], 0, v[2:3]
	global_load_lds_dword v[2:3], off
	s_add_i32 m0, s85, 0x10100
	s_nop 0
	global_load_lds_dword v[4:5], off
.Ldiff_nw0b:
	v_mov_b32_e32 v2, v208
	s_add_i32 s1, s35, s84
	v_lshlrev_b32_e32 v3, 1, v2
	v_and_b32_e32 v4, 8, v3
	v_lshrrev_b32_e32 v3, 1, v2
	v_and_b32_e32 v5, 4, v3
	v_and_b32_e32 v6, 19, v2
	v_or3_b32 v4, v4, v6, v5
	v_bfe_u32 v0, v2, 5, 1
	v_lshrrev_b32_e32 v5, 1, v4
	v_bitop3_b32 v5, v5, v0, 7 bitop3:0x6c
	v_lshl_add_u32 v144, v4, 7, s1
	v_lshlrev_b32_e32 v145, 4, v5
	v_add_u32_e32 v146, v144, v145
	s_branch .Ldiff_after_f1
